# v4 plus: prefetch next dv-slice of state_delta in sample delta units; scan loop back-edge vmcnt(0) relaxed to vmcnt(4)
# baseline (speedup 1.0000x reference)
; __device__ __forceinline__ float delta_prep(const Params& p, int l, int h, bool isP, int grow0, int t0, int nvalid, int bb, char* sm) {
;     ...
;   const float Glast = misc[63];
;   {
;     const float eg = misc[128 + rl];
;     const float ek = __expf(Glast - misc[rl]);
;     bfraw* qg = (bfraw*)(sm + L_QG);
;     bfraw* kgT = (bfraw*)(sm + L_KGT);
;     float t[16];
; #pragma unroll
;     for (int e = 0; e < 16; ++e) t[e] = qf[e] * eg;
;     *(uint4*)(qg + rl * 136 + cg8 * 16) = pack8(t); *(uint4*)(qg + rl * 136 + cg8 * 16 + 8) = pack8(t + 8);
; #pragma unroll
;     for (int e = 0; e < 16; ++e) kgT[(cg8 * 16 + e) * 72 + rl] = f2bf(kf[e] * ek);
;   }
;   const float gl = expf(Glast);
;   __syncthreads();
;   return gl;
; __device__ __forceinline__ void sample_delta_unit(const Params& p, int l, int su, char* sm) {
;     ...
;   const float* S0 = p.state_delta + ((size_t)(l * NBS + bb) * 4 + h) * 128 * 128;
;   float* S1 = p.out + O_DELTAS + ((size_t)(l * NBS + bb) * 4 + h) * 128 * 128;
; #pragma unroll 1
;   for (int s = 0; s < 4; ++s) {
;     f32x4 S[2], o;
;     load_S2(S, S0, s);
.LBB0_1467:
	s_or_b64 exec, exec, s[0:1]
	v_mov_b32_e32 v0, s47
	ds_read_b32 v10, v0
	ds_read2st64_b32 v[0:1], v39 offset1:2
	s_lshl_b32 s0, s38, 1
	s_and_b32 s11, s0, -8
	s_and_b32 s0, s53, 3
	s_lshl_b32 s0, s0, 8
	s_waitcnt lgkmcnt(0)
	v_sub_f32_e32 v0, v10, v0
	v_mul_f32_e32 v0, 0x3fb8aa3b, v0
	v_exp_f32_e32 v11, v0
	v_mov_b32_e32 v0, v1
	v_pk_mul_f32 v[4:5], v[82:83], v[0:1] op_sel_hi:[1,0]
	v_pk_mul_f32 v[6:7], v[78:79], v[0:1] op_sel_hi:[1,0]
	v_cvt_pk_bf16_f32 v4, v4, v5
	v_cvt_pk_bf16_f32 v5, v6, v7
	v_pk_mul_f32 v[6:7], v[74:75], v[0:1] op_sel_hi:[1,0]
	v_pk_mul_f32 v[8:9], v[70:71], v[0:1] op_sel_hi:[1,0]
	v_cvt_pk_bf16_f32 v6, v6, v7
	v_cvt_pk_bf16_f32 v7, v8, v9
	ds_write_b128 v38, v[4:7] offset:17408
	v_pk_mul_f32 v[4:5], v[80:81], v[0:1] op_sel_hi:[1,0]
	v_pk_mul_f32 v[6:7], v[76:77], v[0:1] op_sel_hi:[1,0]
	v_cvt_pk_bf16_f32 v4, v4, v5
	v_cvt_pk_bf16_f32 v5, v6, v7
	v_pk_mul_f32 v[6:7], v[72:73], v[0:1] op_sel_hi:[1,0]
	v_pk_mul_f32 v[0:1], v[68:69], v[0:1] op_sel_hi:[1,0]
	v_cvt_pk_bf16_f32 v6, v6, v7
	v_cvt_pk_bf16_f32 v7, v0, v1
	v_lshlrev_b32_e32 v0, 1, v3
	v_mul_f32_e32 v1, v66, v11
	v_mul_u32_u24_e32 v3, 0x90, v65
	v_cvt_pk_bf16_f32 v1, v1, s0
	v_add3_u32 v0, 0, v0, v3
	ds_write_b128 v38, v[4:7] offset:17424
	ds_write_b16 v0, v1 offset:34816
	v_mul_f32_e32 v1, v67, v11
	v_cvt_pk_bf16_f32 v1, v1, s0
	ds_write_b16 v0, v1 offset:34960
	v_mul_f32_e32 v1, v96, v11
	v_cvt_pk_bf16_f32 v1, v1, s0
	ds_write_b16 v0, v1 offset:35104
	v_mul_f32_e32 v1, v97, v11
	v_cvt_pk_bf16_f32 v1, v1, s0
	ds_write_b16 v0, v1 offset:35248
	v_mul_f32_e32 v1, v94, v11
	v_cvt_pk_bf16_f32 v1, v1, s0
	ds_write_b16 v0, v1 offset:35392
	v_mul_f32_e32 v1, v95, v11
	v_cvt_pk_bf16_f32 v1, v1, s0
	ds_write_b16 v0, v1 offset:35536
	v_mul_f32_e32 v1, v92, v11
	v_cvt_pk_bf16_f32 v1, v1, s0
	ds_write_b16 v0, v1 offset:35680
	v_mul_f32_e32 v1, v93, v11
	v_cvt_pk_bf16_f32 v1, v1, s0
	ds_write_b16 v0, v1 offset:35824
	v_mul_f32_e32 v1, v90, v11
	v_cvt_pk_bf16_f32 v1, v1, s0
	ds_write_b16 v0, v1 offset:35968
	v_mul_f32_e32 v1, v91, v11
	v_cvt_pk_bf16_f32 v1, v1, s0
	ds_write_b16 v0, v1 offset:36112
	v_mul_f32_e32 v1, v88, v11
	v_cvt_pk_bf16_f32 v1, v1, s0
	ds_write_b16 v0, v1 offset:36256
	v_mul_f32_e32 v1, v89, v11
	v_cvt_pk_bf16_f32 v1, v1, s0
	ds_write_b16 v0, v1 offset:36400
	v_mul_f32_e32 v1, v86, v11
	v_cvt_pk_bf16_f32 v1, v1, s0
	ds_write_b16 v0, v1 offset:36544
	v_mul_f32_e32 v1, v87, v11
	v_cvt_pk_bf16_f32 v1, v1, s0
	ds_write_b16 v0, v1 offset:36688
	v_mul_f32_e32 v1, v84, v11
	v_cvt_pk_bf16_f32 v1, v1, s0
	ds_write_b16 v0, v1 offset:36832
	v_mul_f32_e32 v1, 0x3fb8aa3b, v10
	v_fma_f32 v3, v10, s48, -v1
	v_rndne_f32_e32 v4, v1
	v_fmac_f32_e32 v3, 0x32a5705f, v10
	v_sub_f32_e32 v1, v1, v4
	v_readlane_b32 s2, v247, 60
	v_add_f32_e32 v1, v1, v3
	v_readlane_b32 s3, v247, 61
	s_add_u32 s8, s2, s0
	v_exp_f32_e32 v1, v1
	v_cvt_i32_f32_e32 v3, v4
	v_mul_f32_e32 v4, v85, v11
	s_addc_u32 s9, s3, 0
	v_cvt_pk_bf16_f32 v4, v4, s0
	s_and_b32 s0, s56, 0x1fc
	s_or_b32 s0, s0, s57
	v_readlane_b32 s56, v247, 7
	s_lshl_b32 s2, s0, 16
	v_readlane_b32 s64, v247, 15
	ds_write_b16 v0, v4 offset:36976
	v_ldexp_f32 v0, v1, v3
	v_cmp_ngt_f32_e32 vcc, s49, v10
	v_readlane_b32 s65, v247, 16
	s_add_u32 s0, s64, s2
	v_cndmask_b32_e32 v0, 0, v0, vcc
	v_cmp_nlt_f32_e32 vcc, s50, v10
	s_addc_u32 s1, s65, 0
	s_add_u32 s2, s36, s2
	v_cndmask_b32_e32 v0, v159, v0, vcc
	s_addc_u32 s3, s37, 0
	v_mov_b32_e32 v20, v0
	v_mov_b32_e32 v21, v0
	s_add_i32 s10, 0, 0xf400
	s_add_i32 s11, s11, 0x8040
	s_mov_b64 s[4:5], 0
	s_mov_b32 s12, 0
	v_and_b32_e32 v177, 15, v224
	v_lshlrev_b32_e32 v176, 5, v224
	v_and_or_b32 v178, v176, s96, v177
	v_ashrrev_i32_e32 v179, 31, v178
	v_lshl_add_u64 v[178:179], v[178:179], 2, s[0:1]
	global_load_dword v168, v[178:179], off
	global_load_dword v169, v[178:179], off offset:512
	global_load_dword v170, v[178:179], off offset:1024
	global_load_dword v171, v[178:179], off offset:1536
	global_load_dword v172, v[178:179], off offset:64
	global_load_dword v173, v[178:179], off offset:576
	global_load_dword v174, v[178:179], off offset:1088
	global_load_dword v175, v[178:179], off offset:1600
	s_waitcnt lgkmcnt(0)
	s_barrier
	v_readlane_b32 s57, v247, 8
	v_readlane_b32 s58, v247, 9
	v_readlane_b32 s59, v247, 10
	v_readlane_b32 s60, v247, 11
	v_readlane_b32 s61, v247, 12
	v_readlane_b32 s62, v247, 13
	v_readlane_b32 s63, v247, 14
	v_readlane_b32 s66, v247, 17
	v_readlane_b32 s67, v247, 18
	v_readlane_b32 s68, v247, 19
	v_readlane_b32 s69, v247, 20
	v_readlane_b32 s70, v247, 21
	v_readlane_b32 s71, v247, 22
	s_branch .LBB0_1469

; __device__ __forceinline__ float lo2f(unsigned u) { return __uint_as_float(u << 16); }
; __device__ __forceinline__ float hi2f(unsigned u) { return __uint_as_float(u & 0xffff0000u); }
; __device__ __forceinline__ int opq(int x) { asm volatile("" : "+v"(x)); return x; }
; __device__ __forceinline__ void step_part1(char* sm, int off_ut, f32x4& o) {
;   const int tid_ = opq(threadIdx.x);
;   const int lane = tid_ & 63, w = tid_ >> 6, r = lane & 15, q = lane >> 4;
;   const int mj = w >> 1, nd = w & 1;
;   const bfraw* wl = (const bfraw*)(sm + L_W);
;   const bfraw* qg = (const bfraw*)(sm + L_QG);
;   const bfraw* uT = (const bfraw*)(sm + off_ut);
;   const bfraw* St = (const bfraw*)(sm + L_ST);
;   bfraw* dltT = (bfraw*)(sm + L_DLT);
;   f32x4 dl = (f32x4){0.f, 0.f, 0.f, 0.f};
;   o = (f32x4){0.f, 0.f, 0.f, 0.f};
; #pragma unroll
;   for (int kk = 0; kk < 4; ++kk) {
;     bf16x8 sb = *(const bf16x8*)(St + (nd * 16 + r) * 136 + kk * 32 + q * 8);
;     bf16x8 aw = *(const bf16x8*)(wl + (mj * 16 + r) * 136 + kk * 32 + q * 8);
;     bf16x8 aq = *(const bf16x8*)(qg + (mj * 16 + r) * 136 + kk * 32 + q * 8);
;     dl = mfma16(aw, sb, dl);
;     o = mfma16(aq, sb, o);
;   }
;   uint2 uv = *(const uint2*)(uT + (nd * 16 + r) * 72 + mj * 16 + q * 4);
;   uint2 dv;
;   dv.x = pack2(lo2f(uv.x) - dl[0], hi2f(uv.x) - dl[1]);
;   dv.y = pack2(lo2f(uv.y) - dl[2], hi2f(uv.y) - dl[3]);
;   *(uint2*)(dltT + (nd * 16 + r) * 72 + mj * 16 + q * 4) = dv;
; }
; __device__ __forceinline__ void sample_delta_unit(const Params& p, int l, int su, char* sm) {
;     ...
; #pragma unroll 1
;   for (int s = 0; s < 4; ++s) {
;     f32x4 S[2], o;
;     load_S2(S, S0, s);
;     write_St2(S, sm);
;     __syncthreads();
;     step_part1(sm, L_UT + s * 32 * 144, o);
.LBB0_1469:
	v_mov_b32_e32 v1, v224
	s_movk_i32 s6, 0xffe0
	v_and_b32_e32 v3, 15, v1
	v_lshlrev_b32_e32 v1, 5, v1
	v_and_or_b32 v1, v1, s96, v3
	v_add_u32_e32 v4, s12, v1
	v_mov_b32_e32 v1, v224
	v_ashrrev_i32_e32 v5, 31, v4
	v_lshl_add_u64 v[4:5], v[4:5], 2, s[0:1]
	s_waitcnt vmcnt(0)
	v_mov_b32_e32 v8, v168
	v_mov_b32_e32 v9, v169
	v_mov_b32_e32 v10, v170
	v_mov_b32_e32 v11, v171
	v_mov_b32_e32 v12, v172
	v_mov_b32_e32 v13, v173
	v_mov_b32_e32 v14, v174
	v_mov_b32_e32 v15, v175
	s_cmpk_eq_i32 s4, 0xc0
	s_cbranch_scc1 .Lsdp0_nopf
	global_load_dword v168, v[4:5], off offset:128
	global_load_dword v169, v[4:5], off offset:640
	global_load_dword v170, v[4:5], off offset:1152
	global_load_dword v171, v[4:5], off offset:1664
	global_load_dword v172, v[4:5], off offset:192
	global_load_dword v173, v[4:5], off offset:704
	global_load_dword v174, v[4:5], off offset:1216
	global_load_dword v175, v[4:5], off offset:1728
.Lsdp0_nopf:
	v_cvt_pk_bf16_f32 v5, v10, v11
	v_ashrrev_i32_e32 v4, 2, v1
	v_lshlrev_b32_e32 v4, 1, v4
	v_and_b32_e32 v3, 15, v1
	v_and_b32_e32 v4, 0xffffffe0, v4
	v_lshrrev_b32_e32 v1, 1, v1
	v_add_u32_e32 v4, s44, v4
	v_and_b32_e32 v1, 24, v1
	v_mul_u32_u24_e32 v3, 0x110, v3
	v_add3_u32 v1, v4, v1, v3
	v_cvt_pk_bf16_f32 v4, v8, v9
	ds_write_b64 v1, v[4:5]
	v_cvt_pk_bf16_f32 v5, v14, v15
	v_cvt_pk_bf16_f32 v4, v12, v13
	ds_write_b64 v1, v[4:5] offset:4352
	v_mov_b32_e32 v1, v224
	s_waitcnt lgkmcnt(0)
	s_barrier
	v_pk_mul_f32 v[8:9], v[20:21], v[8:9]
	v_and_b32_e32 v3, 15, v1
	v_lshrrev_b32_e32 v5, 2, v1
	v_bfe_u32 v4, v1, 4, 2
	v_and_or_b32 v3, v5, 16, v3
	v_ashrrev_i32_e32 v36, 3, v1
	v_mul_u32_u24_e32 v5, 0x110, v3
	v_lshlrev_b32_e32 v34, 3, v4
	v_lshlrev_b32_e32 v4, 4, v4
	v_bfi_b32 v1, -16, v36, v1
	v_add3_u32 v35, s44, v5, v4
	v_mul_lo_u32 v1, v1, s46
	v_add3_u32 v1, 0, v1, v4
	ds_read_b128 v[4:7], v35
	ds_read_b128 v[16:19], v1
	ds_read_b128 v[22:25], v1 offset:17408
	s_waitcnt lgkmcnt(1)
	v_mfma_f32_16x16x32_bf16 v[16:19], v[16:19], v[4:7], 0
	v_and_b32_e32 v37, -16, v36
	v_pk_mul_f32 v[12:13], v[20:21], v[12:13]
	s_waitcnt lgkmcnt(0)
	v_mfma_f32_16x16x32_bf16 v[4:7], v[22:25], v[4:7], 0
	ds_read_b128 v[22:25], v35 offset:64
	ds_read_b128 v[26:29], v1 offset:64
	ds_read_b128 v[30:33], v1 offset:17472
	s_waitcnt lgkmcnt(1)
	v_mfma_f32_16x16x32_bf16 v[16:19], v[26:29], v[22:25], v[16:19]
	s_waitcnt lgkmcnt(0)
	v_mfma_f32_16x16x32_bf16 v[4:7], v[30:33], v[22:25], v[4:7]
	ds_read_b128 v[22:25], v35 offset:128
	ds_read_b128 v[26:29], v1 offset:128
	ds_read_b128 v[30:33], v1 offset:17536
	s_waitcnt lgkmcnt(1)
	v_mfma_f32_16x16x32_bf16 v[16:19], v[26:29], v[22:25], v[16:19]
	s_waitcnt lgkmcnt(0)
	v_mfma_f32_16x16x32_bf16 v[4:7], v[30:33], v[22:25], v[4:7]
	ds_read_b128 v[22:25], v35 offset:192
	ds_read_b128 v[26:29], v1 offset:192
	ds_read_b128 v[30:33], v1 offset:17600
	v_mul_u32_u24_e32 v1, 0x48, v3
	v_lshlrev_b32_e32 v3, 1, v36
	v_and_or_b32 v3, v3, s6, v34
	v_lshlrev_b32_e32 v1, 1, v1
	v_add3_u32 v3, v3, v1, s10
	s_waitcnt lgkmcnt(1)
	v_mfma_f32_16x16x32_bf16 v[16:19], v[26:29], v[22:25], v[16:19]
	v_add_u32_e32 v1, s16, v1
	s_waitcnt lgkmcnt(0)
	v_mfma_f32_16x16x32_bf16 v[4:7], v[30:33], v[22:25], v[4:7]
	ds_read_b64 v[22:23], v3
	v_lshlrev_b32_e32 v3, 1, v37
	v_add3_u32 v1, v1, v3, v34
	v_mov_b32_e32 v3, v224
	s_waitcnt lgkmcnt(0)
	v_lshlrev_b32_e32 v24, 16, v22
	v_and_b32_e32 v25, 0xffff0000, v22
	v_lshlrev_b32_e32 v22, 16, v23
	v_and_b32_e32 v23, 0xffff0000, v23
	v_pk_add_f32 v[16:17], v[24:25], v[16:17] neg_lo:[0,1] neg_hi:[0,1]
	v_pk_add_f32 v[18:19], v[22:23], v[18:19] neg_lo:[0,1] neg_hi:[0,1]
	v_cvt_pk_bf16_f32 v16, v16, v17
	v_cvt_pk_bf16_f32 v17, v18, v19
	ds_write_b64 v1, v[16:17]
	s_waitcnt lgkmcnt(0)
	s_barrier
	s_nop 0
	v_and_b32_e32 v22, 15, v3
	v_bfe_u32 v23, v3, 4, 2
	v_mul_u32_u24_e32 v16, 0x90, v22
	v_lshlrev_b32_e32 v25, 4, v23
	v_ashrrev_i32_e32 v1, 6, v3
	v_add3_u32 v17, s16, v16, v25
	v_ashrrev_i32_e32 v16, 3, v3
	v_and_b32_e32 v19, 1, v1
	v_and_b32_e32 v24, -16, v16
	v_bfi_b32 v16, -16, v16, v3
	v_lshl_or_b32 v1, v1, 4, v22
	v_mul_lo_u32 v16, v16, s43
	v_mul_lo_u32 v1, v1, s43
	v_add3_u32 v18, 0, v16, v25
	v_add3_u32 v16, 0, v1, v25
	ds_read_b128 v[26:29], v17
	ds_read_b128 v[30:33], v17 offset:2304
	ds_read_b128 v[34:37], v18 offset:53248
	ds_read_b128 v[38:41], v16 offset:34816
	v_cmp_eq_u32_e32 vcc, 0, v19
	v_mov_b32_e32 v1, v0
	v_pk_mul_f32 v[10:11], v[0:1], v[10:11]
	s_waitcnt lgkmcnt(2)
	v_cndmask_b32_e32 v45, v33, v29, vcc
	v_cndmask_b32_e32 v44, v32, v28, vcc
	v_cndmask_b32_e32 v43, v31, v27, vcc
	v_cndmask_b32_e32 v42, v30, v26, vcc
	v_pk_mul_f32 v[14:15], v[0:1], v[14:15]
	s_waitcnt lgkmcnt(0)
	v_mfma_f32_16x16x32_bf16 v[8:11], v[38:41], v[26:29], v[8:11]
	v_mov_b32_e32 v1, v224
	v_mfma_f32_16x16x32_bf16 v[4:7], v[34:37], v[42:45], v[4:7]
	v_mfma_f32_16x16x32_bf16 v[12:15], v[38:41], v[30:33], v[12:15]
	ds_read_b128 v[26:29], v17 offset:64
	ds_read_b128 v[30:33], v17 offset:2368
	ds_read_b128 v[34:37], v18 offset:53312
	ds_read_b128 v[38:41], v16 offset:34880
	s_waitcnt lgkmcnt(2)
	v_cndmask_b32_e32 v19, v33, v29, vcc
	v_cndmask_b32_e32 v18, v32, v28, vcc
	v_cndmask_b32_e32 v17, v31, v27, vcc
	v_cndmask_b32_e32 v16, v30, v26, vcc
	s_waitcnt lgkmcnt(0)
	v_mfma_f32_16x16x32_bf16 v[8:11], v[38:41], v[26:29], v[8:11]
	v_mfma_f32_16x16x32_bf16 v[16:19], v[34:37], v[16:19], v[4:7]
	v_mfma_f32_16x16x32_bf16 v[4:7], v[38:41], v[30:33], v[12:15]
	s_nop 2
	v_ashrrev_i32_e32 v13, 2, v1
	v_lshlrev_b32_e32 v13, 1, v13
	v_and_b32_e32 v12, 15, v1
	v_and_b32_e32 v13, 0xffffffe0, v13
	v_lshrrev_b32_e32 v1, 1, v1
	v_add_u32_e32 v13, s44, v13
	v_and_b32_e32 v1, 24, v1
	v_mul_u32_u24_e32 v12, 0x110, v12
	v_add3_u32 v1, v13, v1, v12
	v_cvt_pk_bf16_f32 v13, v10, v11
	v_cvt_pk_bf16_f32 v12, v8, v9
	ds_write_b64 v1, v[12:13]
	v_cvt_pk_bf16_f32 v13, v6, v7
	v_cvt_pk_bf16_f32 v12, v4, v5
	ds_write_b64 v1, v[12:13] offset:4352
	v_lshlrev_b32_e32 v1, 2, v23
	v_or_b32_e32 v14, v1, v24
	v_add3_u32 v12, s11, v24, v1
	v_lshrrev_b32_e32 v1, 1, v3
	v_cmp_gt_i32_e32 vcc, 8, v14
	v_ashrrev_i32_e32 v13, 31, v12
	v_and_b32_e32 v1, 32, v1
	v_lshlrev_b32_e32 v3, 1, v22
	s_and_saveexec_b64 s[6:7], vcc
	s_cbranch_execz .LBB0_1471
	v_lshlrev_b64 v[22:23], 12, v[12:13]
	s_add_u32 s18, s8, s4
	v_or3_b32 v22, v22, v1, v3
	s_addc_u32 s19, s9, s5
	v_lshl_add_u64 v[22:23], s[18:19], 0, v[22:23]
	v_add_co_u32_e32 v22, vcc, 0x6420000, v22
	v_cvt_pk_bf16_f32 v15, v16, s0
	s_nop 0
	v_addc_co_u32_e32 v23, vcc, 0, v23, vcc
	global_store_short v[22:23], v15, off

; #define SCAN_STEP(C, KB, GLV) { \
;     __syncthreads(); \
;     int t0_, nv_; \
;     if ((C) == 0) { t0_ = 0; nv_ = 16; } else { t0_ = 16 + ((C) - 1) * 64; nv_ = 64; } \
;     f32x4 o_; \
;     step_part1(sm, L_UT, o_); \
;     __syncthreads(); \
;     step_part2(p, sm, (KB) ? L_KGT2 : L_KGT, (KB) ? L_QK2 : L_QK, h, s, b * TP + t0_, nv_, GLV, o_, S); }
; __device__ __forceinline__ void scan_unit(const Params& p, int l, int bhs, char* sm) {
;     ...
;   for (int c = 0; c < NCH; c += 2) {
;     LDS_PUT(a, 0)
;     const float gl0 = gla;
;     PRE_LOAD(a, gla, c + 2)
;     SCAN_STEP(c, 0, gl0)
;     if (c + 1 < NCH) {
;       LDS_PUT(b, 1)
;       const float gl1 = glb;
;       PRE_LOAD(b, glb, c + 3)
;       SCAN_STEP(c + 1, 1, gl1)
;     }
;   }
.LBB0_1593:
	s_mov_b32 s8, s34
	s_waitcnt vmcnt(4)
	v_mov_b32_e32 v78, v84
	v_mov_b32_e32 v80, v92

; __device__ __forceinline__ float delta_prep(const Params& p, int l, int h, bool isP, int grow0, int t0, int nvalid, int bb, char* sm) {
;     ...
;   const float Glast = misc[63];
;   {
;     const float eg = misc[128 + rl];
;     const float ek = __expf(Glast - misc[rl]);
;     bfraw* qg = (bfraw*)(sm + L_QG);
;     bfraw* kgT = (bfraw*)(sm + L_KGT);
;     float t[16];
; #pragma unroll
;     for (int e = 0; e < 16; ++e) t[e] = qf[e] * eg;
;     *(uint4*)(qg + rl * 136 + cg8 * 16) = pack8(t); *(uint4*)(qg + rl * 136 + cg8 * 16 + 8) = pack8(t + 8);
; #pragma unroll
;     for (int e = 0; e < 16; ++e) kgT[(cg8 * 16 + e) * 72 + rl] = f2bf(kf[e] * ek);
;   }
;   const float gl = expf(Glast);
;   __syncthreads();
;   return gl;
; __device__ __forceinline__ void sample_delta_unit(const Params& p, int l, int su, char* sm) {
;     ...
;   const float* S0 = p.state_delta + ((size_t)(l * NBS + bb) * 4 + h) * 128 * 128;
;   float* S1 = p.out + O_DELTAS + ((size_t)(l * NBS + bb) * 4 + h) * 128 * 128;
; #pragma unroll 1
;   for (int s = 0; s < 4; ++s) {
;     f32x4 S[2], o;
;     load_S2(S, S0, s);
.LBB0_4225:
	s_or_b64 exec, exec, s[0:1]
	s_lshl_b32 s0, s42, 1
	s_and_b32 s11, s0, -8
	v_readlane_b32 s0, v246, 3
	v_readlane_b32 s2, v247, 60
	v_readlane_b32 s3, v247, 61
	v_mov_b32_e32 v0, s0
	ds_read_b32 v10, v0
	ds_read2st64_b32 v[0:1], v39 offset1:2
	s_and_b32 s0, s90, 3
	s_lshl_b32 s0, s0, 8
	s_add_u32 s8, s2, s0
	s_addc_u32 s9, s3, 0
	s_waitcnt lgkmcnt(0)
	v_sub_f32_e32 v0, v10, v0
	v_mul_f32_e32 v0, 0x3fb8aa3b, v0
	v_exp_f32_e32 v11, v0
	v_mov_b32_e32 v0, v1
	v_pk_mul_f32 v[4:5], v[82:83], v[0:1] op_sel_hi:[1,0]
	v_pk_mul_f32 v[6:7], v[78:79], v[0:1] op_sel_hi:[1,0]
	v_cvt_pk_bf16_f32 v4, v4, v5
	v_cvt_pk_bf16_f32 v5, v6, v7
	v_pk_mul_f32 v[6:7], v[74:75], v[0:1] op_sel_hi:[1,0]
	v_pk_mul_f32 v[8:9], v[70:71], v[0:1] op_sel_hi:[1,0]
	v_cvt_pk_bf16_f32 v6, v6, v7
	v_cvt_pk_bf16_f32 v7, v8, v9
	ds_write_b128 v38, v[4:7] offset:17408
	v_pk_mul_f32 v[4:5], v[80:81], v[0:1] op_sel_hi:[1,0]
	v_pk_mul_f32 v[6:7], v[76:77], v[0:1] op_sel_hi:[1,0]
	v_cvt_pk_bf16_f32 v4, v4, v5
	v_cvt_pk_bf16_f32 v5, v6, v7
	v_pk_mul_f32 v[6:7], v[72:73], v[0:1] op_sel_hi:[1,0]
	v_pk_mul_f32 v[0:1], v[68:69], v[0:1] op_sel_hi:[1,0]
	v_cvt_pk_bf16_f32 v6, v6, v7
	v_cvt_pk_bf16_f32 v7, v0, v1
	v_lshlrev_b32_e32 v0, 1, v3
	v_mul_f32_e32 v1, v66, v11
	v_mul_u32_u24_e32 v3, 0x90, v65
	v_cvt_pk_bf16_f32 v1, v1, s0
	v_add3_u32 v0, 0, v0, v3
	ds_write_b128 v38, v[4:7] offset:17424
	ds_write_b16 v0, v1 offset:34816
	v_mul_f32_e32 v1, v67, v11
	v_cvt_pk_bf16_f32 v1, v1, s0
	ds_write_b16 v0, v1 offset:34960
	v_mul_f32_e32 v1, v96, v11
	v_cvt_pk_bf16_f32 v1, v1, s0
	ds_write_b16 v0, v1 offset:35104
	v_mul_f32_e32 v1, v97, v11
	v_cvt_pk_bf16_f32 v1, v1, s0
	ds_write_b16 v0, v1 offset:35248
	v_mul_f32_e32 v1, v94, v11
	v_cvt_pk_bf16_f32 v1, v1, s0
	ds_write_b16 v0, v1 offset:35392
	v_mul_f32_e32 v1, v95, v11
	v_cvt_pk_bf16_f32 v1, v1, s0
	ds_write_b16 v0, v1 offset:35536
	v_mul_f32_e32 v1, v92, v11
	v_cvt_pk_bf16_f32 v1, v1, s0
	ds_write_b16 v0, v1 offset:35680
	v_mul_f32_e32 v1, v93, v11
	v_cvt_pk_bf16_f32 v1, v1, s0
	ds_write_b16 v0, v1 offset:35824
	v_mul_f32_e32 v1, v90, v11
	v_cvt_pk_bf16_f32 v1, v1, s0
	ds_write_b16 v0, v1 offset:35968
	v_mul_f32_e32 v1, v91, v11
	v_cvt_pk_bf16_f32 v1, v1, s0
	ds_write_b16 v0, v1 offset:36112
	v_mul_f32_e32 v1, v88, v11
	v_cvt_pk_bf16_f32 v1, v1, s0
	ds_write_b16 v0, v1 offset:36256
	v_mul_f32_e32 v1, v89, v11
	v_cvt_pk_bf16_f32 v1, v1, s0
	ds_write_b16 v0, v1 offset:36400
	v_mul_f32_e32 v1, v86, v11
	v_cvt_pk_bf16_f32 v1, v1, s0
	ds_write_b16 v0, v1 offset:36544
	v_mul_f32_e32 v1, v87, v11
	v_cvt_pk_bf16_f32 v1, v1, s0
	ds_write_b16 v0, v1 offset:36688
	v_mul_f32_e32 v1, v84, v11
	v_cvt_pk_bf16_f32 v1, v1, s0
	ds_write_b16 v0, v1 offset:36832
	v_mul_f32_e32 v1, 0x3fb8aa3b, v10
	s_mov_b32 s0, 0x3fb8aa3b
	v_fma_f32 v3, v10, s0, -v1
	v_rndne_f32_e32 v4, v1
	v_fmac_f32_e32 v3, 0x32a5705f, v10
	v_sub_f32_e32 v1, v1, v4
	v_add_f32_e32 v1, v1, v3
	v_cvt_i32_f32_e32 v3, v4
	v_mul_f32_e32 v4, v85, v11
	v_cvt_pk_bf16_f32 v4, v4, s0
	s_mov_b32 s0, 0xc2ce8ed0
	v_exp_f32_e32 v1, v1
	v_cmp_ngt_f32_e32 vcc, s0, v10
	s_and_b32 s0, s64, 0x1fc
	s_or_b32 s0, s0, s65
	v_readlane_b32 s12, v247, 7
	s_lshl_b32 s0, s0, 16
	v_readlane_b32 s16, v247, 11
	v_readlane_b32 s17, v247, 12
	v_readlane_b32 s18, v247, 13
	v_readlane_b32 s19, v247, 14
	v_readlane_b32 s20, v247, 15
	v_readlane_b32 s21, v247, 16
	s_or_b32 s2, s0, 0x2000000
	v_readlane_b32 s22, v247, 17
	v_readlane_b32 s23, v247, 18
	v_readlane_b32 s24, v247, 19
	v_readlane_b32 s25, v247, 20
	s_mov_b64 s[16:17], s[20:21]
	ds_write_b16 v0, v4 offset:36976
	v_ldexp_f32 v0, v1, v3
	s_add_u32 s0, s16, s2
	v_cndmask_b32_e32 v0, 0, v0, vcc
	v_cmp_nlt_f32_e32 vcc, s91, v10
	s_addc_u32 s1, s17, 0
	v_readlane_b32 s3, v246, 1
	v_cndmask_b32_e32 v0, v159, v0, vcc
	s_add_u32 s2, s3, s2
	v_readlane_b32 s3, v246, 2
	s_addc_u32 s3, s3, 0
	v_mov_b32_e32 v20, v0
	v_mov_b32_e32 v21, v0
	s_add_i32 s10, 0, 0xf400
	s_add_i32 s11, s11, 0x8040
	s_mov_b64 s[4:5], 0
	s_mov_b32 s12, 0
	v_and_b32_e32 v177, 15, v224
	v_lshlrev_b32_e32 v176, 5, v224
	v_and_or_b32 v178, v176, s95, v177
	v_ashrrev_i32_e32 v179, 31, v178
	v_lshl_add_u64 v[178:179], v[178:179], 2, s[0:1]
	global_load_dword v168, v[178:179], off
	global_load_dword v169, v[178:179], off offset:512
	global_load_dword v170, v[178:179], off offset:1024
	global_load_dword v171, v[178:179], off offset:1536
	global_load_dword v172, v[178:179], off offset:64
	global_load_dword v173, v[178:179], off offset:576
	global_load_dword v174, v[178:179], off offset:1088
	global_load_dword v175, v[178:179], off offset:1600
	s_waitcnt lgkmcnt(0)
	s_barrier
	v_readlane_b32 s13, v247, 8
	v_readlane_b32 s14, v247, 9
	v_readlane_b32 s15, v247, 10
	v_readlane_b32 s26, v247, 21
	v_readlane_b32 s27, v247, 22
	s_mov_b64 s[18:19], s[22:23]
	s_mov_b64 s[20:21], s[24:25]
	s_branch .LBB0_4227

; __device__ __forceinline__ float lo2f(unsigned u) { return __uint_as_float(u << 16); }
; __device__ __forceinline__ float hi2f(unsigned u) { return __uint_as_float(u & 0xffff0000u); }
; __device__ __forceinline__ int opq(int x) { asm volatile("" : "+v"(x)); return x; }
; __device__ __forceinline__ void step_part1(char* sm, int off_ut, f32x4& o) {
;   const int tid_ = opq(threadIdx.x);
;   const int lane = tid_ & 63, w = tid_ >> 6, r = lane & 15, q = lane >> 4;
;   const int mj = w >> 1, nd = w & 1;
;   const bfraw* wl = (const bfraw*)(sm + L_W);
;   const bfraw* qg = (const bfraw*)(sm + L_QG);
;   const bfraw* uT = (const bfraw*)(sm + off_ut);
;   const bfraw* St = (const bfraw*)(sm + L_ST);
;   bfraw* dltT = (bfraw*)(sm + L_DLT);
;   f32x4 dl = (f32x4){0.f, 0.f, 0.f, 0.f};
;   o = (f32x4){0.f, 0.f, 0.f, 0.f};
; #pragma unroll
;   for (int kk = 0; kk < 4; ++kk) {
;     bf16x8 sb = *(const bf16x8*)(St + (nd * 16 + r) * 136 + kk * 32 + q * 8);
;     bf16x8 aw = *(const bf16x8*)(wl + (mj * 16 + r) * 136 + kk * 32 + q * 8);
;     bf16x8 aq = *(const bf16x8*)(qg + (mj * 16 + r) * 136 + kk * 32 + q * 8);
;     dl = mfma16(aw, sb, dl);
;     o = mfma16(aq, sb, o);
;   }
;   uint2 uv = *(const uint2*)(uT + (nd * 16 + r) * 72 + mj * 16 + q * 4);
;   uint2 dv;
;   dv.x = pack2(lo2f(uv.x) - dl[0], hi2f(uv.x) - dl[1]);
;   dv.y = pack2(lo2f(uv.y) - dl[2], hi2f(uv.y) - dl[3]);
;   *(uint2*)(dltT + (nd * 16 + r) * 72 + mj * 16 + q * 4) = dv;
; }
; __device__ __forceinline__ void sample_delta_unit(const Params& p, int l, int su, char* sm) {
;     ...
; #pragma unroll 1
;   for (int s = 0; s < 4; ++s) {
;     f32x4 S[2], o;
;     load_S2(S, S0, s);
;     write_St2(S, sm);
;     __syncthreads();
;     step_part1(sm, L_UT + s * 32 * 144, o);
.LBB0_4227:
	v_mov_b32_e32 v1, v224
	s_movk_i32 s6, 0xffe0
	v_and_b32_e32 v3, 15, v1
	v_lshlrev_b32_e32 v1, 5, v1
	v_and_or_b32 v1, v1, s95, v3
	v_add_u32_e32 v4, s12, v1
	v_mov_b32_e32 v1, v224
	v_ashrrev_i32_e32 v5, 31, v4
	v_lshl_add_u64 v[4:5], v[4:5], 2, s[0:1]
	s_waitcnt vmcnt(0)
	v_mov_b32_e32 v8, v168
	v_mov_b32_e32 v9, v169
	v_mov_b32_e32 v10, v170
	v_mov_b32_e32 v11, v171
	v_mov_b32_e32 v12, v172
	v_mov_b32_e32 v13, v173
	v_mov_b32_e32 v14, v174
	v_mov_b32_e32 v15, v175
	s_cmpk_eq_i32 s4, 0xc0
	s_cbranch_scc1 .Lsdp1_nopf
	global_load_dword v168, v[4:5], off offset:128
	global_load_dword v169, v[4:5], off offset:640
	global_load_dword v170, v[4:5], off offset:1152
	global_load_dword v171, v[4:5], off offset:1664
	global_load_dword v172, v[4:5], off offset:192
	global_load_dword v173, v[4:5], off offset:704
	global_load_dword v174, v[4:5], off offset:1216
	global_load_dword v175, v[4:5], off offset:1728
.Lsdp1_nopf:
	v_cvt_pk_bf16_f32 v5, v10, v11
	v_ashrrev_i32_e32 v4, 2, v1
	v_lshlrev_b32_e32 v4, 1, v4
	v_and_b32_e32 v3, 15, v1
	v_and_b32_e32 v4, 0xffffffe0, v4
	v_lshrrev_b32_e32 v1, 1, v1
	v_add_u32_e32 v4, s48, v4
	v_and_b32_e32 v1, 24, v1
	v_mul_u32_u24_e32 v3, 0x110, v3
	v_add3_u32 v1, v4, v1, v3
	v_cvt_pk_bf16_f32 v4, v8, v9
	ds_write_b64 v1, v[4:5]
	v_cvt_pk_bf16_f32 v5, v14, v15
	v_cvt_pk_bf16_f32 v4, v12, v13
	ds_write_b64 v1, v[4:5] offset:4352
	v_mov_b32_e32 v1, v224
	s_waitcnt lgkmcnt(0)
	s_barrier
	v_pk_mul_f32 v[8:9], v[20:21], v[8:9]
	v_and_b32_e32 v3, 15, v1
	v_lshrrev_b32_e32 v5, 2, v1
	v_bfe_u32 v4, v1, 4, 2
	v_and_or_b32 v3, v5, 16, v3
	v_ashrrev_i32_e32 v36, 3, v1
	v_mul_u32_u24_e32 v5, 0x110, v3
	v_lshlrev_b32_e32 v34, 3, v4
	v_lshlrev_b32_e32 v4, 4, v4
	v_bfi_b32 v1, -16, v36, v1
	v_add3_u32 v35, s48, v5, v4
	v_mul_lo_u32 v1, v1, s50
	v_add3_u32 v1, 0, v1, v4
	ds_read_b128 v[4:7], v35
	ds_read_b128 v[16:19], v1
	ds_read_b128 v[22:25], v1 offset:17408
	s_waitcnt lgkmcnt(1)
	v_mfma_f32_16x16x32_bf16 v[16:19], v[16:19], v[4:7], 0
	v_and_b32_e32 v37, -16, v36
	v_pk_mul_f32 v[12:13], v[20:21], v[12:13]
	s_waitcnt lgkmcnt(0)
	v_mfma_f32_16x16x32_bf16 v[4:7], v[22:25], v[4:7], 0
	ds_read_b128 v[22:25], v35 offset:64
	ds_read_b128 v[26:29], v1 offset:64
	ds_read_b128 v[30:33], v1 offset:17472
	s_waitcnt lgkmcnt(1)
	v_mfma_f32_16x16x32_bf16 v[16:19], v[26:29], v[22:25], v[16:19]
	s_waitcnt lgkmcnt(0)
	v_mfma_f32_16x16x32_bf16 v[4:7], v[30:33], v[22:25], v[4:7]
	ds_read_b128 v[22:25], v35 offset:128
	ds_read_b128 v[26:29], v1 offset:128
	ds_read_b128 v[30:33], v1 offset:17536
	s_waitcnt lgkmcnt(1)
	v_mfma_f32_16x16x32_bf16 v[16:19], v[26:29], v[22:25], v[16:19]
	s_waitcnt lgkmcnt(0)
	v_mfma_f32_16x16x32_bf16 v[4:7], v[30:33], v[22:25], v[4:7]
	ds_read_b128 v[22:25], v35 offset:192
	ds_read_b128 v[26:29], v1 offset:192
	ds_read_b128 v[30:33], v1 offset:17600
	v_mul_u32_u24_e32 v1, 0x48, v3
	v_lshlrev_b32_e32 v3, 1, v36
	v_and_or_b32 v3, v3, s6, v34
	v_lshlrev_b32_e32 v1, 1, v1
	v_add3_u32 v3, v3, v1, s10
	s_waitcnt lgkmcnt(1)
	v_mfma_f32_16x16x32_bf16 v[16:19], v[26:29], v[22:25], v[16:19]
	v_add_u32_e32 v1, s97, v1
	s_waitcnt lgkmcnt(0)
	v_mfma_f32_16x16x32_bf16 v[4:7], v[30:33], v[22:25], v[4:7]
	ds_read_b64 v[22:23], v3
	v_lshlrev_b32_e32 v3, 1, v37
	v_add3_u32 v1, v1, v3, v34
	v_mov_b32_e32 v3, v224
	s_waitcnt lgkmcnt(0)
	v_lshlrev_b32_e32 v24, 16, v22
	v_and_b32_e32 v25, 0xffff0000, v22
	v_lshlrev_b32_e32 v22, 16, v23
	v_and_b32_e32 v23, 0xffff0000, v23
	v_pk_add_f32 v[16:17], v[24:25], v[16:17] neg_lo:[0,1] neg_hi:[0,1]
	v_pk_add_f32 v[18:19], v[22:23], v[18:19] neg_lo:[0,1] neg_hi:[0,1]
	v_cvt_pk_bf16_f32 v16, v16, v17
	v_cvt_pk_bf16_f32 v17, v18, v19
	ds_write_b64 v1, v[16:17]
	s_waitcnt lgkmcnt(0)
	s_barrier
	s_nop 0
	v_and_b32_e32 v22, 15, v3
	v_bfe_u32 v23, v3, 4, 2
	v_mul_u32_u24_e32 v16, 0x90, v22
	v_lshlrev_b32_e32 v25, 4, v23
	v_ashrrev_i32_e32 v1, 6, v3
	v_add3_u32 v17, s97, v16, v25
	v_ashrrev_i32_e32 v16, 3, v3
	v_and_b32_e32 v19, 1, v1
	v_and_b32_e32 v24, -16, v16
	v_bfi_b32 v16, -16, v16, v3
	v_lshl_or_b32 v1, v1, 4, v22
	v_mul_lo_u32 v16, v16, s47
	v_mul_lo_u32 v1, v1, s47
	v_add3_u32 v18, 0, v16, v25
	v_add3_u32 v16, 0, v1, v25
	ds_read_b128 v[26:29], v17
	ds_read_b128 v[30:33], v17 offset:2304
	ds_read_b128 v[34:37], v18 offset:53248
	ds_read_b128 v[38:41], v16 offset:34816
	v_cmp_eq_u32_e32 vcc, 0, v19
	v_mov_b32_e32 v1, v0
	v_pk_mul_f32 v[10:11], v[0:1], v[10:11]
	s_waitcnt lgkmcnt(2)
	v_cndmask_b32_e32 v45, v33, v29, vcc
	v_cndmask_b32_e32 v44, v32, v28, vcc
	v_cndmask_b32_e32 v43, v31, v27, vcc
	v_cndmask_b32_e32 v42, v30, v26, vcc
	v_pk_mul_f32 v[14:15], v[0:1], v[14:15]
	s_waitcnt lgkmcnt(0)
	v_mfma_f32_16x16x32_bf16 v[8:11], v[38:41], v[26:29], v[8:11]
	v_mov_b32_e32 v1, v224
	v_mfma_f32_16x16x32_bf16 v[4:7], v[34:37], v[42:45], v[4:7]
	v_mfma_f32_16x16x32_bf16 v[12:15], v[38:41], v[30:33], v[12:15]
	ds_read_b128 v[26:29], v17 offset:64
	ds_read_b128 v[30:33], v17 offset:2368
	ds_read_b128 v[34:37], v18 offset:53312
	ds_read_b128 v[38:41], v16 offset:34880
	s_waitcnt lgkmcnt(2)
	v_cndmask_b32_e32 v19, v33, v29, vcc
	v_cndmask_b32_e32 v18, v32, v28, vcc
	v_cndmask_b32_e32 v17, v31, v27, vcc
	v_cndmask_b32_e32 v16, v30, v26, vcc
	s_waitcnt lgkmcnt(0)
	v_mfma_f32_16x16x32_bf16 v[8:11], v[38:41], v[26:29], v[8:11]
	v_mfma_f32_16x16x32_bf16 v[16:19], v[34:37], v[16:19], v[4:7]
	v_mfma_f32_16x16x32_bf16 v[4:7], v[38:41], v[30:33], v[12:15]
	s_nop 2
	v_ashrrev_i32_e32 v13, 2, v1
	v_lshlrev_b32_e32 v13, 1, v13
	v_and_b32_e32 v12, 15, v1
	v_and_b32_e32 v13, 0xffffffe0, v13
	v_lshrrev_b32_e32 v1, 1, v1
	v_add_u32_e32 v13, s48, v13
	v_and_b32_e32 v1, 24, v1
	v_mul_u32_u24_e32 v12, 0x110, v12
	v_add3_u32 v1, v13, v1, v12
	v_cvt_pk_bf16_f32 v13, v10, v11
	v_cvt_pk_bf16_f32 v12, v8, v9
	ds_write_b64 v1, v[12:13]
	v_cvt_pk_bf16_f32 v13, v6, v7
	v_cvt_pk_bf16_f32 v12, v4, v5
	ds_write_b64 v1, v[12:13] offset:4352
	v_lshlrev_b32_e32 v1, 2, v23
	v_or_b32_e32 v14, v1, v24
	v_add3_u32 v12, s11, v24, v1
	v_lshrrev_b32_e32 v1, 1, v3
	v_cmp_gt_i32_e32 vcc, 8, v14
	v_ashrrev_i32_e32 v13, 31, v12
	v_and_b32_e32 v1, 32, v1
	v_lshlrev_b32_e32 v3, 1, v22
	s_and_saveexec_b64 s[6:7], vcc
	s_cbranch_execz .LBB0_4229
	v_lshlrev_b64 v[22:23], 12, v[12:13]
	s_add_u32 s18, s8, s4
	v_or3_b32 v22, v22, v1, v3
	s_addc_u32 s19, s9, s5
	v_lshl_add_u64 v[22:23], s[18:19], 0, v[22:23]
	v_add_co_u32_e32 v22, vcc, 0x6420000, v22
	v_cvt_pk_bf16_f32 v15, v16, s0
	s_nop 0
	v_addc_co_u32_e32 v23, vcc, 0, v23, vcc
	global_store_short v[22:23], v15, off
